# MoBA past-block steps: 16 v_max3_f32 (4 chains) replace 53 canonicalize+max instructions for the per-lane score maximum
# baseline (speedup 1.0000x reference)
; #define LAS __attribute__((address_space(3)))
; __device__ __forceinline__ float fexp2(float x) { return __builtin_amdgcn_exp2f(x); }
; __device__ __forceinline__ void qk_tile(LAS const unsigned char* Kb, const bf16x8 (&qr)[4], int r32, int hi, f32x16& p0, f32x16& p1) {
; #pragma unroll
;     for (int r = 0; r < 16; ++r) { p0[r] = 0.f; p1[r] = 0.f; }
; #pragma unroll
;     for (int d0 = 0; d0 < 4; ++d0) {
;         const bf16x8 k0 = *(LAS const bf16x8*)(Kb + r32 * KP + d0 * 32 + hi * 16);
;         const bf16x8 k1 = *(LAS const bf16x8*)(Kb + (32 + r32) * KP + d0 * 32 + hi * 16);
;         p0 = MFMA32(k0, qr[d0], p0); p1 = MFMA32(k1, qr[d0], p1);
;     }
; }
; __device__ __forceinline__ void pv_tile(LAS const unsigned char* Vb, int lane, const f32x16& p0, const f32x16& p1, f32x16 (&o)[2]) {
;     const int i = lane & 15, q4 = i >> 2, pp = i & 3, g1 = (lane >> 4) & 1, hi = lane >> 5;
;     LAS const unsigned char* vb = Vb + (4 * hi + q4) * KP + g1 * 32 + pp * 8;
; #pragma unroll
;     for (int sub = 0; sub < 2; ++sub)
; #pragma unroll
;         for (int s = 0; s < 2; ++s) {
;             u32x4 pk;
;             if (sub == 0) { pk.x = cvtpk(p0[8 * s], p0[8 * s + 1]); pk.y = cvtpk(p0[8 * s + 2], p0[8 * s + 3]); pk.z = cvtpk(p0[8 * s + 4], p0[8 * s + 5]); pk.w = cvtpk(p0[8 * s + 6], p0[8 * s + 7]); }
; template <bool DIAG> __device__ __forceinline__ void moba_softmax(f32x16& p0, f32x16& p1, int t, int qrel, int hi, int lane, bool mysel, float C, float& mrun, float& lrun, f32x16 (&o)[2]) {
;     float bias = 0.f;
;     if (DIAG) {
; #pragma unroll
;         for (int r = 0; r < 16; ++r) { const int kv = 64 * t + crow(r, hi); p0[r] = kv <= qrel ? p0[r] : -INFINITY; p1[r] = kv + 32 <= qrel ? p1[r] : -INFINITY; }
;     } else bias = mysel ? 0.f : -INFINITY;
;     float rm = fmaxf(p0[0], p1[0]);
; #pragma unroll
;     for (int r = 1; r < 16; ++r) rm = fmaxf(rm, fmaxf(p0[r], p1[r]));
;     rm = fmaxf(rm, shx(rm, 32, lane));
;     const float mnew = fmaxf(mrun, rm * C + bias); const float alpha = fexp2(mrun - mnew);
; #pragma unroll
;     for (int r = 0; r < 16; ++r) { o[0][r] *= alpha; o[1][r] *= alpha; }
;     mrun = mnew; const float nb = bias - mnew; float rs = 0.f;
; #pragma unroll
;     for (int r = 0; r < 16; ++r) { p0[r] = fexp2(__builtin_fmaf(p0[r], C, nb)); p1[r] = fexp2(__builtin_fmaf(p1[r], C, nb)); rs += p0[r] + p1[r]; }
;     lrun = lrun * alpha + rs;
.LBB0_470:
	s_cmp_gt_u32 s16, 3
	s_cselect_b64 s[2:3], -1, 0
	s_mov_b64 s[8:9], -1
	s_and_b64 vcc, exec, s[2:3]
	v_add_u32_e32 v221, s11, v214
	v_max_f32_e32 v220, v213, v213
	v_add_u32_e32 v219, s10, v215
	s_cbranch_vccz .LBB0_472
	ds_read_b128 v[66:69], v221
	s_add_i32 s8, s16, -4
	s_lshr_b32 s8, s8, 2
	ds_read_b128 v[86:89], v221 offset:32
	ds_read_b128 v[82:85], v221 offset:4608
	ds_read_b128 v[102:105], v221 offset:4640
	ds_read_b128 v[90:93], v221 offset:64
	ds_read_b128 v[98:101], v221 offset:4672
	ds_read_b128 v[94:97], v221 offset:96
	ds_read_b128 v[162:165], v221 offset:4704
	s_waitcnt lgkmcnt(7)
	v_mfma_f32_32x32x16_bf16 v[66:81], v[66:69], v[142:145], 0
	v_bfe_u32 v0, v209, s8, 1
	v_cmp_eq_u32_e32 vcc, 0, v0
	v_max3_f32 v0, v34, v35, v36
	v_max3_f32 v106, v37, v38, v39
	v_max3_f32 v107, v40, v41, v42
	v_max3_f32 v108, v43, v44, v45
	v_max3_f32 v0, v0, v46, v47
	v_max3_f32 v106, v106, v48, v49
	v_max3_f32 v107, v107, v50, v51
	v_max3_f32 v108, v108, v52, v53
	v_max3_f32 v0, v0, v54, v55
	v_max3_f32 v106, v106, v56, v57
	v_max3_f32 v107, v107, v58, v59
	v_max3_f32 v108, v108, v60, v61
	v_max3_f32 v0, v0, v62, v63
	v_max3_f32 v106, v106, v64, v65
	v_max3_f32 v0, v0, v106, v107
	v_max_f32_e32 v0, v0, v108
	s_waitcnt lgkmcnt(6)
	v_mfma_f32_32x32x16_bf16 v[66:81], v[86:89], v[138:141], v[66:81]
	s_waitcnt lgkmcnt(3)
	v_mfma_f32_32x32x16_bf16 v[66:81], v[90:93], v[134:137], v[66:81]
	ds_bpermute_b32 v86, v169, v0
	v_cndmask_b32_e32 v87, 0, v235, vcc
	ds_read_b64_tr_b16 v[238:239], v219 offset:27648
	ds_read_b64_tr_b16 v[240:241], v219 offset:28800
	s_mov_b64 s[8:9], 0
	s_waitcnt lgkmcnt(2)
	v_max_f32_e32 v86, v86, v86
	v_max_f32_e32 v0, v0, v86
	v_fmamk_f32 v0, v0, 0x3e38aa3b, v87
	v_max_f32_e32 v216, v220, v0
	v_mfma_f32_32x32x16_bf16 v[66:81], v[94:97], v[130:133], v[66:81]
	v_sub_f32_e32 v106, v87, v216
	v_fmamk_f32 v87, v38, 0x3e38aa3b, v106
	v_exp_f32_e32 v109, v87
	v_fmamk_f32 v87, v54, 0x3e38aa3b, v106
	v_fmamk_f32 v0, v34, 0x3e38aa3b, v106
	v_fmamk_f32 v86, v36, 0x3e38aa3b, v106
	v_exp_f32_e32 v189, v87
	v_fmamk_f32 v87, v40, 0x3e38aa3b, v106
	v_exp_f32_e32 v107, v0
	v_fmamk_f32 v0, v50, 0x3e38aa3b, v106
	v_exp_f32_e32 v108, v86
	v_fmamk_f32 v86, v52, 0x3e38aa3b, v106
	v_exp_f32_e32 v110, v87
	v_fmamk_f32 v87, v56, 0x3e38aa3b, v106
	v_exp_f32_e32 v181, v0
	v_exp_f32_e32 v185, v86
	v_fmamk_f32 v86, v37, 0x3e38aa3b, v106
	v_exp_f32_e32 v195, v87
	v_exp_f32_e32 v176, v86
	v_fmamk_f32 v86, v53, 0x3e38aa3b, v106
	v_sub_f32_e32 v0, v213, v216
	v_exp_f32_e32 v180, v86
	v_fmamk_f32 v86, v39, 0x3e38aa3b, v106
	v_exp_f32_e32 v172, v0
	v_fmamk_f32 v0, v35, 0x3e38aa3b, v106
	v_exp_f32_e32 v178, v86
	v_fmamk_f32 v86, v55, 0x3e38aa3b, v106
	v_add_f32_e32 v175, v107, v181
	v_exp_f32_e32 v174, v0
	v_fmamk_f32 v0, v51, 0x3e38aa3b, v106
	v_add_f32_e32 v177, v108, v185
	v_add_f32_e32 v179, v109, v189
	v_exp_f32_e32 v184, v86
	v_add_f32_e32 v183, v110, v195
	v_mfma_f32_32x32x16_bf16 v[82:97], v[82:85], v[142:145], 0
	v_fmamk_f32 v111, v41, 0x3e38aa3b, v106
	v_fmamk_f32 v113, v58, 0x3e38aa3b, v106
	v_exp_f32_e32 v182, v111
	v_fmamk_f32 v111, v57, 0x3e38aa3b, v106
	v_fmamk_f32 v114, v60, 0x3e38aa3b, v106
	v_fmamk_f32 v115, v62, 0x3e38aa3b, v106
	v_fmamk_f32 v112, v42, 0x3e38aa3b, v106
	v_exp_f32_e32 v197, v113
	v_exp_f32_e32 v188, v111
	v_fmamk_f32 v111, v43, 0x3e38aa3b, v106
	v_fmamk_f32 v113, v44, 0x3e38aa3b, v106
	v_exp_f32_e32 v201, v114
	v_fmamk_f32 v114, v46, 0x3e38aa3b, v106
	v_exp_f32_e32 v203, v115
	v_fmamk_f32 v115, v48, 0x3e38aa3b, v106
	v_fmamk_f32 v116, v64, 0x3e38aa3b, v106
	v_exp_f32_e32 v112, v112
	v_exp_f32_e32 v113, v113
	v_exp_f32_e32 v186, v111
	v_fmamk_f32 v111, v59, 0x3e38aa3b, v106
	v_exp_f32_e32 v114, v114
	v_exp_f32_e32 v115, v115
	v_exp_f32_e32 v217, v116
	v_exp_f32_e32 v194, v111
	v_fmamk_f32 v111, v45, 0x3e38aa3b, v106
	v_exp_f32_e32 v192, v111
	v_fmamk_f32 v111, v61, 0x3e38aa3b, v106
	v_exp_f32_e32 v196, v111
	v_fmamk_f32 v111, v47, 0x3e38aa3b, v106
	v_add_f32_e32 v187, v112, v197
	v_add_f32_e32 v193, v113, v201
	v_add_f32_e32 v191, v114, v203
	v_exp_f32_e32 v190, v111
	v_fmamk_f32 v111, v63, 0x3e38aa3b, v106
	v_add_f32_e32 v199, v115, v217
	v_mfma_f32_32x32x16_bf16 v[82:97], v[102:105], v[138:141], v[82:97]
	v_fmamk_f32 v102, v49, 0x3e38aa3b, v106
	v_exp_f32_e32 v198, v102
	v_exp_f32_e32 v200, v111
	v_fmac_f32_e32 v106, 0x3e38aa3b, v65
	v_cvt_pk_bf16_f32 v222, v107, v174
	v_cvt_pk_bf16_f32 v223, v108, v176
	v_cvt_pk_bf16_f32 v224, v109, v178
	v_cvt_pk_bf16_f32 v225, v110, v182
	v_cvt_pk_bf16_f32 v242, v112, v186
	v_cvt_pk_bf16_f32 v243, v113, v192
	v_cvt_pk_bf16_f32 v244, v114, v190
	v_cvt_pk_bf16_f32 v245, v115, v198
	v_pk_mul_f32 v[128:129], v[32:33], v[172:173] op_sel_hi:[1,0]
	v_pk_mul_f32 v[126:127], v[30:31], v[172:173] op_sel_hi:[1,0]
	v_pk_mul_f32 v[124:125], v[28:29], v[172:173] op_sel_hi:[1,0]
	v_pk_mul_f32 v[122:123], v[26:27], v[172:173] op_sel_hi:[1,0]
	v_pk_mul_f32 v[120:121], v[24:25], v[172:173] op_sel_hi:[1,0]
	v_pk_mul_f32 v[118:119], v[22:23], v[172:173] op_sel_hi:[1,0]
	v_pk_mul_f32 v[116:117], v[20:21], v[172:173] op_sel_hi:[1,0]
	v_pk_mul_f32 v[114:115], v[18:19], v[172:173] op_sel_hi:[1,0]
	v_pk_mul_f32 v[112:113], v[16:17], v[172:173] op_sel_hi:[1,0]
	v_pk_mul_f32 v[110:111], v[14:15], v[172:173] op_sel_hi:[1,0]
	v_mfma_f32_32x32x16_bf16 v[82:97], v[98:101], v[134:137], v[82:97]
	v_exp_f32_e32 v0, v0
	v_exp_f32_e32 v202, v106
	v_pk_mul_f32 v[108:109], v[12:13], v[172:173] op_sel_hi:[1,0]
	v_pk_mul_f32 v[106:107], v[10:11], v[172:173] op_sel_hi:[1,0]
	v_pk_mul_f32 v[104:105], v[8:9], v[172:173] op_sel_hi:[1,0]
	v_pk_mul_f32 v[102:103], v[6:7], v[172:173] op_sel_hi:[1,0]
	v_pk_mul_f32 v[100:101], v[4:5], v[172:173] op_sel_hi:[1,0]
	v_pk_mul_f32 v[98:99], v[2:3], v[172:173] op_sel_hi:[1,0]
	v_cvt_pk_bf16_f32 v246, v181, v0
	v_cvt_pk_bf16_f32 v247, v185, v180
	v_cvt_pk_bf16_f32 v248, v189, v184
	v_cvt_pk_bf16_f32 v249, v195, v188
	v_cvt_pk_bf16_f32 v250, v197, v194
	v_cvt_pk_bf16_f32 v251, v201, v196
	v_cvt_pk_bf16_f32 v252, v203, v200
	v_cvt_pk_bf16_f32 v253, v217, v202
	v_mfma_f32_32x32x16_bf16 v[82:97], v[162:165], v[130:133], v[82:97]
	ds_read_b64_tr_b16 v[162:163], v219 offset:27712
	ds_read_b64_tr_b16 v[164:165], v219 offset:28864
	v_add_f32_e64 v174, v174, v0
	v_add_f32_e64 v175, v175, v1
	v_pk_add_f32 v[174:175], v[174:175], v[174:175] op_sel_hi:[0,1]
	v_mov_b32_e32 v181, v175
	s_waitcnt lgkmcnt(2)
; #define LAS __attribute__((address_space(3)))
; __device__ __forceinline__ unsigned cvtpk(float lo, float hi) { f32x2_t v = {lo, hi}; bf16x2_t b = __builtin_convertvector(v, bf16x2_t); return __builtin_bit_cast(unsigned, b); }
; __device__ __forceinline__ float fexp2(float x) { return __builtin_amdgcn_exp2f(x); }
; #define MFMA32(a, b, c) __builtin_amdgcn_mfma_f32_32x32x16_bf16((a), (b), (c), 0, 0, 0)
; __device__ __forceinline__ s16x4 vtr(LAS const unsigned char* p) { typedef short v4i16_t __attribute__((ext_vector_type(4))); return __builtin_bit_cast(s16x4, __builtin_amdgcn_ds_read_tr16_b64_v4i16((LAS v4i16_t*)p)); }
; __device__ __forceinline__ void pv_tile(LAS const unsigned char* Vb, int lane, const f32x16& p0, const f32x16& p1, f32x16 (&o)[2]) {
;     const int i = lane & 15, q4 = i >> 2, pp = i & 3, g1 = (lane >> 4) & 1, hi = lane >> 5;
;     LAS const unsigned char* vb = Vb + (4 * hi + q4) * KP + g1 * 32 + pp * 8;
; #pragma unroll
;     for (int sub = 0; sub < 2; ++sub)
; #pragma unroll
;         for (int s = 0; s < 2; ++s) {
;             u32x4 pk;
;             if (sub == 0) { pk.x = cvtpk(p0[8 * s], p0[8 * s + 1]); pk.y = cvtpk(p0[8 * s + 2], p0[8 * s + 3]); pk.z = cvtpk(p0[8 * s + 4], p0[8 * s + 5]); pk.w = cvtpk(p0[8 * s + 6], p0[8 * s + 7]); }
;             else          { pk.x = cvtpk(p1[8 * s], p1[8 * s + 1]); pk.y = cvtpk(p1[8 * s + 2], p1[8 * s + 3]); pk.z = cvtpk(p1[8 * s + 4], p1[8 * s + 5]); pk.w = cvtpk(p1[8 * s + 6], p1[8 * s + 7]); }
;             const bf16x8 pb = __builtin_bit_cast(bf16x8, pk);
; #pragma unroll
;             for (int d0 = 0; d0 < 2; ++d0) {
;                 const s16x4 lo = vtr(vb + (32 * sub + 16 * s) * KP + d0 * 64);
;                 const s16x4 hh = vtr(vb + (32 * sub + 16 * s + 8) * KP + d0 * 64);
;                 const bf16x8 va = {lo[0], lo[1], lo[2], lo[3], hh[0], hh[1], hh[2], hh[3]};
;                 o[d0] = MFMA32(va, pb, o[d0]);
;             }
;         }
; template <bool DIAG> __device__ __forceinline__ void moba_softmax(f32x16& p0, f32x16& p1, int t, int qrel, int hi, int lane, bool mysel, float C, float& mrun, float& lrun, f32x16 (&o)[2]) {
;     ...
;     for (int r = 0; r < 16; ++r) { p0[r] = fexp2(__builtin_fmaf(p0[r], C, nb)); p1[r] = fexp2(__builtin_fmaf(p1[r], C, nb)); rs += p0[r] + p1[r]; }
;     lrun = lrun * alpha + rs;
	v_mfma_f32_32x32x16_bf16 v[114:129], v[238:241], v[222:225], v[114:129]
	ds_read_b64_tr_b16 v[238:239], v219 offset:29952
	ds_read_b64_tr_b16 v[240:241], v219 offset:31104
	v_add_f32_e64 v174, v176, v180
	v_add_f32_e64 v175, v177, v181
	v_pk_add_f32 v[174:175], v[174:175], v[174:175] op_sel_hi:[0,1]
	v_mov_b32_e32 v185, v175
	v_pk_add_f32 v[174:175], v[178:179], v[184:185]
	s_waitcnt lgkmcnt(2)
	v_mfma_f32_32x32x16_bf16 v[98:113], v[162:165], v[222:225], v[98:113]
	ds_read_b64_tr_b16 v[162:163], v219 offset:30016
	ds_read_b64_tr_b16 v[164:165], v219 offset:31168
	ds_read_b64_tr_b16 v[222:223], v219 offset:32256
	ds_read_b64_tr_b16 v[224:225], v219 offset:33408
	v_pk_add_f32 v[174:175], v[174:175], v[174:175] op_sel_hi:[0,1]
	v_mov_b32_e32 v189, v175
	v_pk_add_f32 v[174:175], v[182:183], v[188:189]
	s_waitcnt lgkmcnt(4)
	v_mfma_f32_32x32x16_bf16 v[114:129], v[238:241], v[242:245], v[114:129]
	ds_read_b64_tr_b16 v[238:239], v219 offset:32320
	ds_read_b64_tr_b16 v[240:241], v219 offset:33472
	v_pk_add_f32 v[174:175], v[174:175], v[174:175] op_sel_hi:[0,1]
	v_mov_b32_e32 v195, v175
	v_pk_add_f32 v[174:175], v[186:187], v[194:195]
	s_nop 0
	v_pk_add_f32 v[174:175], v[174:175], v[174:175] op_sel_hi:[0,1]
	s_waitcnt lgkmcnt(4)
	v_mfma_f32_32x32x16_bf16 v[98:113], v[162:165], v[242:245], v[98:113]
	ds_read_b64_tr_b16 v[162:163], v219 offset:34560
	ds_read_b64_tr_b16 v[164:165], v219 offset:35712
	ds_read_b64_tr_b16 v[242:243], v219 offset:34624
	ds_read_b64_tr_b16 v[244:245], v219 offset:35776
	v_mov_b32_e32 v197, v175
	v_pk_add_f32 v[174:175], v[192:193], v[196:197]
	s_waitcnt lgkmcnt(6)
	v_mfma_f32_32x32x16_bf16 v[114:129], v[222:225], v[246:249], v[114:129]
	v_pk_add_f32 v[174:175], v[174:175], v[174:175] op_sel_hi:[0,1]
	v_mov_b32_e32 v201, v175
	s_waitcnt lgkmcnt(4)
	v_mfma_f32_32x32x16_bf16 v[98:113], v[238:241], v[246:249], v[98:113]
	s_waitcnt lgkmcnt(2)
	v_mfma_f32_32x32x16_bf16 v[114:129], v[162:165], v[250:253], v[114:129]
	v_add_f32_e64 v162, v190, v200
	v_add_f32_e64 v163, v191, v201
	v_pk_add_f32 v[162:163], v[162:163], v[162:163] op_sel_hi:[0,1]
	v_mov_b32_e32 v203, v163
	v_pk_add_f32 v[162:163], v[198:199], v[202:203]
	s_nop 0
	v_add_f32_e32 v218, v162, v163
	v_fmac_f32_e32 v218, v210, v172
	s_waitcnt lgkmcnt(0)
	v_mfma_f32_32x32x16_bf16 v[98:113], v[242:245], v[250:253], v[98:113]

; #define LAS __attribute__((address_space(3)))
; __device__ __forceinline__ float fexp2(float x) { return __builtin_amdgcn_exp2f(x); }
; __device__ __forceinline__ void qk_tile(LAS const unsigned char* Kb, const bf16x8 (&qr)[4], int r32, int hi, f32x16& p0, f32x16& p1) {
; #pragma unroll
;     for (int r = 0; r < 16; ++r) { p0[r] = 0.f; p1[r] = 0.f; }
; #pragma unroll
;     for (int d0 = 0; d0 < 4; ++d0) {
;         const bf16x8 k0 = *(LAS const bf16x8*)(Kb + r32 * KP + d0 * 32 + hi * 16);
;         const bf16x8 k1 = *(LAS const bf16x8*)(Kb + (32 + r32) * KP + d0 * 32 + hi * 16);
;         p0 = MFMA32(k0, qr[d0], p0); p1 = MFMA32(k1, qr[d0], p1);
;     }
; }
; __device__ __forceinline__ void pv_tile(LAS const unsigned char* Vb, int lane, const f32x16& p0, const f32x16& p1, f32x16 (&o)[2]) {
;     const int i = lane & 15, q4 = i >> 2, pp = i & 3, g1 = (lane >> 4) & 1, hi = lane >> 5;
;     LAS const unsigned char* vb = Vb + (4 * hi + q4) * KP + g1 * 32 + pp * 8;
; #pragma unroll
;     for (int sub = 0; sub < 2; ++sub)
; #pragma unroll
;         for (int s = 0; s < 2; ++s) {
;             u32x4 pk;
;             if (sub == 0) { pk.x = cvtpk(p0[8 * s], p0[8 * s + 1]); pk.y = cvtpk(p0[8 * s + 2], p0[8 * s + 3]); pk.z = cvtpk(p0[8 * s + 4], p0[8 * s + 5]); pk.w = cvtpk(p0[8 * s + 6], p0[8 * s + 7]); }
; template <bool DIAG> __device__ __forceinline__ void moba_softmax(f32x16& p0, f32x16& p1, int t, int qrel, int hi, int lane, bool mysel, float C, float& mrun, float& lrun, f32x16 (&o)[2]) {
;     float bias = 0.f;
;     if (DIAG) {
; #pragma unroll
;         for (int r = 0; r < 16; ++r) { const int kv = 64 * t + crow(r, hi); p0[r] = kv <= qrel ? p0[r] : -INFINITY; p1[r] = kv + 32 <= qrel ? p1[r] : -INFINITY; }
;     } else bias = mysel ? 0.f : -INFINITY;
;     float rm = fmaxf(p0[0], p1[0]);
; #pragma unroll
;     for (int r = 1; r < 16; ++r) rm = fmaxf(rm, fmaxf(p0[r], p1[r]));
;     rm = fmaxf(rm, shx(rm, 32, lane));
;     const float mnew = fmaxf(mrun, rm * C + bias); const float alpha = fexp2(mrun - mnew);
; #pragma unroll
;     for (int r = 0; r < 16; ++r) { o[0][r] *= alpha; o[1][r] *= alpha; }
;     mrun = mnew; const float nb = bias - mnew; float rs = 0.f;
; #pragma unroll
;     for (int r = 0; r < 16; ++r) { p0[r] = fexp2(__builtin_fmaf(p0[r], C, nb)); p1[r] = fexp2(__builtin_fmaf(p1[r], C, nb)); rs += p0[r] + p1[r]; }
;     lrun = lrun * alpha + rs;
.LBB0_476:
	s_mov_b64 s[8:9], -1
	s_and_b64 vcc, exec, s[2:3]
	v_add_u32_e32 v221, s4, v214
	v_max_f32_e32 v220, v216, v216
	v_add_u32_e32 v219, s11, v215
	s_cbranch_vccz .LBB0_482
	ds_read_b128 v[14:17], v221
	s_add_i32 s2, s16, -3
	s_lshr_b32 s2, s2, 2
	ds_read_b128 v[18:21], v221 offset:32
	ds_read_b128 v[10:13], v221 offset:4608
	ds_read_b128 v[6:9], v221 offset:4640
	ds_read_b128 v[22:25], v221 offset:64
	ds_read_b128 v[2:5], v221 offset:4672
	ds_read_b128 v[26:29], v221 offset:96
	ds_read_b128 v[162:165], v221 offset:4704
	s_waitcnt lgkmcnt(7)
	v_mfma_f32_32x32x16_bf16 v[34:49], v[14:17], v[142:145], 0
	v_bfe_u32 v0, v209, s2, 1
	v_cmp_eq_u32_e32 vcc, 0, v0
	v_max3_f32 v0, v66, v67, v68
	v_max3_f32 v14, v69, v70, v71
	v_max3_f32 v15, v72, v73, v74
	v_max3_f32 v16, v75, v76, v77
	v_max3_f32 v0, v0, v78, v79
	v_max3_f32 v14, v14, v80, v81
	v_max3_f32 v15, v15, v82, v83
	v_max3_f32 v16, v16, v84, v85
	v_max3_f32 v0, v0, v86, v87
	v_max3_f32 v14, v14, v88, v89
	v_max3_f32 v15, v15, v90, v91
	v_max3_f32 v16, v16, v92, v93
	v_max3_f32 v0, v0, v94, v95
	v_max3_f32 v14, v14, v96, v97
	v_max3_f32 v0, v0, v14, v15
	v_max_f32_e32 v0, v0, v16
	s_waitcnt lgkmcnt(6)
	v_mfma_f32_32x32x16_bf16 v[34:49], v[18:21], v[138:141], v[34:49]
	s_waitcnt lgkmcnt(3)
	v_mfma_f32_32x32x16_bf16 v[34:49], v[22:25], v[134:137], v[34:49]
	ds_bpermute_b32 v14, v169, v0
	v_cndmask_b32_e32 v15, 0, v235, vcc
	ds_read_b64_tr_b16 v[238:239], v219 offset:27648
	ds_read_b64_tr_b16 v[240:241], v219 offset:28800
	s_waitcnt lgkmcnt(2)
	v_max_f32_e32 v14, v14, v14
	v_max_f32_e32 v0, v0, v14
	v_fmamk_f32 v0, v0, 0x3e38aa3b, v15
	v_max_f32_e32 v213, v220, v0
	v_mfma_f32_32x32x16_bf16 v[34:49], v[26:29], v[130:133], v[34:49]
	v_sub_f32_e32 v14, v15, v213
	v_fmamk_f32 v0, v66, 0x3e38aa3b, v14
	v_fmamk_f32 v19, v86, 0x3e38aa3b, v14
	v_exp_f32_e32 v15, v0
	v_fmamk_f32 v0, v82, 0x3e38aa3b, v14
	v_fmamk_f32 v16, v68, 0x3e38aa3b, v14
	v_fmamk_f32 v17, v84, 0x3e38aa3b, v14
	v_fmamk_f32 v18, v70, 0x3e38aa3b, v14
	v_exp_f32_e32 v189, v19
	v_fmamk_f32 v19, v72, 0x3e38aa3b, v14
	v_fmamk_f32 v20, v88, 0x3e38aa3b, v14
	v_exp_f32_e32 v181, v0
	v_exp_f32_e32 v16, v16
	v_exp_f32_e32 v185, v17
	v_exp_f32_e32 v18, v18
	v_exp_f32_e32 v19, v19
	v_exp_f32_e32 v195, v20
	v_fmamk_f32 v17, v69, 0x3e38aa3b, v14
	v_sub_f32_e32 v0, v216, v213
	v_exp_f32_e32 v176, v17
	v_fmamk_f32 v17, v85, 0x3e38aa3b, v14
	v_exp_f32_e32 v172, v0
	v_fmamk_f32 v0, v67, 0x3e38aa3b, v14
	v_exp_f32_e32 v180, v17
	v_fmamk_f32 v17, v71, 0x3e38aa3b, v14
	v_add_f32_e32 v175, v15, v181
	v_exp_f32_e32 v174, v0
	v_fmamk_f32 v0, v83, 0x3e38aa3b, v14
	v_add_f32_e32 v177, v16, v185
	v_add_f32_e32 v179, v18, v189
	v_exp_f32_e32 v178, v17
	v_fmamk_f32 v17, v87, 0x3e38aa3b, v14
	v_add_f32_e32 v183, v19, v195
	v_mfma_f32_32x32x16_bf16 v[50:65], v[10:13], v[142:145], 0
	v_fmamk_f32 v10, v73, 0x3e38aa3b, v14
	v_exp_f32_e32 v184, v17
	v_fmamk_f32 v12, v90, 0x3e38aa3b, v14
	v_exp_f32_e32 v182, v10
	v_fmamk_f32 v10, v89, 0x3e38aa3b, v14
	v_fmamk_f32 v13, v92, 0x3e38aa3b, v14
	v_fmamk_f32 v17, v94, 0x3e38aa3b, v14
	v_fmamk_f32 v11, v74, 0x3e38aa3b, v14
	v_exp_f32_e32 v197, v12
	v_exp_f32_e32 v188, v10
	v_fmamk_f32 v10, v75, 0x3e38aa3b, v14
	v_fmamk_f32 v12, v76, 0x3e38aa3b, v14
	v_exp_f32_e32 v201, v13
	v_fmamk_f32 v13, v78, 0x3e38aa3b, v14
	v_exp_f32_e32 v203, v17
	v_fmamk_f32 v17, v80, 0x3e38aa3b, v14
	v_fmamk_f32 v20, v96, 0x3e38aa3b, v14
	v_exp_f32_e32 v11, v11
	v_exp_f32_e32 v12, v12
	v_exp_f32_e32 v186, v10
	v_fmamk_f32 v10, v91, 0x3e38aa3b, v14
	v_exp_f32_e32 v13, v13
	v_exp_f32_e32 v17, v17
	v_exp_f32_e32 v210, v20
	v_exp_f32_e32 v194, v10
	v_fmamk_f32 v10, v77, 0x3e38aa3b, v14
	v_exp_f32_e32 v192, v10
	v_fmamk_f32 v10, v93, 0x3e38aa3b, v14
	v_exp_f32_e32 v196, v10
	v_fmamk_f32 v10, v79, 0x3e38aa3b, v14
	v_add_f32_e32 v187, v11, v197
	v_add_f32_e32 v193, v12, v201
	v_add_f32_e32 v191, v13, v203
	v_exp_f32_e32 v190, v10
	v_fmamk_f32 v10, v95, 0x3e38aa3b, v14
	v_add_f32_e32 v199, v17, v210
	v_mfma_f32_32x32x16_bf16 v[50:65], v[6:9], v[138:141], v[50:65]
	v_fmamk_f32 v6, v81, 0x3e38aa3b, v14
	v_exp_f32_e32 v198, v6
	v_fmac_f32_e32 v14, 0x3e38aa3b, v97
	v_exp_f32_e32 v202, v14
	v_cvt_pk_bf16_f32 v222, v15, v174
	v_cvt_pk_bf16_f32 v223, v16, v176
	v_cvt_pk_bf16_f32 v224, v18, v178
	v_cvt_pk_bf16_f32 v225, v19, v182
	v_cvt_pk_bf16_f32 v242, v11, v186
	v_cvt_pk_bf16_f32 v243, v12, v192
	v_cvt_pk_bf16_f32 v244, v13, v190
	v_cvt_pk_bf16_f32 v245, v17, v198
	v_pk_mul_f32 v[32:33], v[128:129], v[172:173] op_sel_hi:[1,0]
	v_pk_mul_f32 v[30:31], v[126:127], v[172:173] op_sel_hi:[1,0]
	v_pk_mul_f32 v[28:29], v[124:125], v[172:173] op_sel_hi:[1,0]
	v_pk_mul_f32 v[26:27], v[122:123], v[172:173] op_sel_hi:[1,0]
	v_pk_mul_f32 v[24:25], v[120:121], v[172:173] op_sel_hi:[1,0]
	v_pk_mul_f32 v[22:23], v[118:119], v[172:173] op_sel_hi:[1,0]
	v_pk_mul_f32 v[20:21], v[116:117], v[172:173] op_sel_hi:[1,0]
	v_pk_mul_f32 v[18:19], v[114:115], v[172:173] op_sel_hi:[1,0]
	v_pk_mul_f32 v[16:17], v[112:113], v[172:173] op_sel_hi:[1,0]
	v_pk_mul_f32 v[14:15], v[110:111], v[172:173] op_sel_hi:[1,0]
	v_mfma_f32_32x32x16_bf16 v[50:65], v[2:5], v[134:137], v[50:65]
	v_exp_f32_e32 v0, v0
	v_exp_f32_e32 v200, v10
	v_pk_mul_f32 v[12:13], v[108:109], v[172:173] op_sel_hi:[1,0]
	v_pk_mul_f32 v[10:11], v[106:107], v[172:173] op_sel_hi:[1,0]
	v_pk_mul_f32 v[8:9], v[104:105], v[172:173] op_sel_hi:[1,0]
	v_pk_mul_f32 v[6:7], v[102:103], v[172:173] op_sel_hi:[1,0]
	v_pk_mul_f32 v[4:5], v[100:101], v[172:173] op_sel_hi:[1,0]
	v_pk_mul_f32 v[2:3], v[98:99], v[172:173] op_sel_hi:[1,0]
	v_cvt_pk_bf16_f32 v246, v181, v0
	v_cvt_pk_bf16_f32 v247, v185, v180
	v_cvt_pk_bf16_f32 v248, v189, v184
	v_cvt_pk_bf16_f32 v249, v195, v188
	v_cvt_pk_bf16_f32 v250, v197, v194
	v_cvt_pk_bf16_f32 v251, v201, v196
	v_cvt_pk_bf16_f32 v252, v203, v200
	v_cvt_pk_bf16_f32 v253, v210, v202
	v_mfma_f32_32x32x16_bf16 v[50:65], v[162:165], v[130:133], v[50:65]
	ds_read_b64_tr_b16 v[162:163], v219 offset:27712
	ds_read_b64_tr_b16 v[164:165], v219 offset:28864
	v_add_f32_e64 v174, v174, v0
	v_add_f32_e64 v175, v175, v1
	v_pk_add_f32 v[174:175], v[174:175], v[174:175] op_sel_hi:[0,1]
	v_mov_b32_e32 v181, v175
	s_waitcnt lgkmcnt(2)
; #define LAS __attribute__((address_space(3)))
; __device__ __forceinline__ unsigned cvtpk(float lo, float hi) { f32x2_t v = {lo, hi}; bf16x2_t b = __builtin_convertvector(v, bf16x2_t); return __builtin_bit_cast(unsigned, b); }
; __device__ __forceinline__ float fexp2(float x) { return __builtin_amdgcn_exp2f(x); }
; #define MFMA32(a, b, c) __builtin_amdgcn_mfma_f32_32x32x16_bf16((a), (b), (c), 0, 0, 0)
; __device__ __forceinline__ s16x4 vtr(LAS const unsigned char* p) { typedef short v4i16_t __attribute__((ext_vector_type(4))); return __builtin_bit_cast(s16x4, __builtin_amdgcn_ds_read_tr16_b64_v4i16((LAS v4i16_t*)p)); }
; __device__ __forceinline__ void pv_tile(LAS const unsigned char* Vb, int lane, const f32x16& p0, const f32x16& p1, f32x16 (&o)[2]) {
;     const int i = lane & 15, q4 = i >> 2, pp = i & 3, g1 = (lane >> 4) & 1, hi = lane >> 5;
;     LAS const unsigned char* vb = Vb + (4 * hi + q4) * KP + g1 * 32 + pp * 8;
; #pragma unroll
;     for (int sub = 0; sub < 2; ++sub)
; #pragma unroll
;         for (int s = 0; s < 2; ++s) {
;             u32x4 pk;
;             if (sub == 0) { pk.x = cvtpk(p0[8 * s], p0[8 * s + 1]); pk.y = cvtpk(p0[8 * s + 2], p0[8 * s + 3]); pk.z = cvtpk(p0[8 * s + 4], p0[8 * s + 5]); pk.w = cvtpk(p0[8 * s + 6], p0[8 * s + 7]); }
;             else          { pk.x = cvtpk(p1[8 * s], p1[8 * s + 1]); pk.y = cvtpk(p1[8 * s + 2], p1[8 * s + 3]); pk.z = cvtpk(p1[8 * s + 4], p1[8 * s + 5]); pk.w = cvtpk(p1[8 * s + 6], p1[8 * s + 7]); }
;             const bf16x8 pb = __builtin_bit_cast(bf16x8, pk);
; #pragma unroll
;             for (int d0 = 0; d0 < 2; ++d0) {
;                 const s16x4 lo = vtr(vb + (32 * sub + 16 * s) * KP + d0 * 64);
;                 const s16x4 hh = vtr(vb + (32 * sub + 16 * s + 8) * KP + d0 * 64);
;                 const bf16x8 va = {lo[0], lo[1], lo[2], lo[3], hh[0], hh[1], hh[2], hh[3]};
;                 o[d0] = MFMA32(va, pb, o[d0]);
;             }
;         }
; template <bool DIAG> __device__ __forceinline__ void moba_softmax(f32x16& p0, f32x16& p1, int t, int qrel, int hi, int lane, bool mysel, float C, float& mrun, float& lrun, f32x16 (&o)[2]) {
;     ...
;     for (int r = 0; r < 16; ++r) { p0[r] = fexp2(__builtin_fmaf(p0[r], C, nb)); p1[r] = fexp2(__builtin_fmaf(p1[r], C, nb)); rs += p0[r] + p1[r]; }
;     lrun = lrun * alpha + rs;
	v_mfma_f32_32x32x16_bf16 v[18:33], v[238:241], v[222:225], v[18:33]
	ds_read_b64_tr_b16 v[238:239], v219 offset:29952
	ds_read_b64_tr_b16 v[240:241], v219 offset:31104
	v_add_f32_e64 v174, v176, v180
	v_add_f32_e64 v175, v177, v181
	v_pk_add_f32 v[174:175], v[174:175], v[174:175] op_sel_hi:[0,1]
	v_mov_b32_e32 v185, v175
	v_pk_add_f32 v[174:175], v[178:179], v[184:185]
	s_waitcnt lgkmcnt(2)
	v_mfma_f32_32x32x16_bf16 v[2:17], v[162:165], v[222:225], v[2:17]
	ds_read_b64_tr_b16 v[162:163], v219 offset:30016
	ds_read_b64_tr_b16 v[164:165], v219 offset:31168
	ds_read_b64_tr_b16 v[222:223], v219 offset:32256
	ds_read_b64_tr_b16 v[224:225], v219 offset:33408
	v_pk_add_f32 v[174:175], v[174:175], v[174:175] op_sel_hi:[0,1]
	v_mov_b32_e32 v189, v175
	v_pk_add_f32 v[174:175], v[182:183], v[188:189]
	s_waitcnt lgkmcnt(4)
	v_mfma_f32_32x32x16_bf16 v[18:33], v[238:241], v[242:245], v[18:33]
	ds_read_b64_tr_b16 v[238:239], v219 offset:32320
	ds_read_b64_tr_b16 v[240:241], v219 offset:33472
	v_pk_add_f32 v[174:175], v[174:175], v[174:175] op_sel_hi:[0,1]
	v_mov_b32_e32 v195, v175
	v_pk_add_f32 v[174:175], v[186:187], v[194:195]
	s_nop 0
	v_pk_add_f32 v[174:175], v[174:175], v[174:175] op_sel_hi:[0,1]
	s_waitcnt lgkmcnt(4)
	v_mfma_f32_32x32x16_bf16 v[2:17], v[162:165], v[242:245], v[2:17]
	ds_read_b64_tr_b16 v[162:163], v219 offset:34560
	ds_read_b64_tr_b16 v[164:165], v219 offset:35712
	ds_read_b64_tr_b16 v[242:243], v219 offset:34624
	ds_read_b64_tr_b16 v[244:245], v219 offset:35776
	v_mov_b32_e32 v197, v175
	v_pk_add_f32 v[174:175], v[192:193], v[196:197]
	s_waitcnt lgkmcnt(6)
	v_mfma_f32_32x32x16_bf16 v[18:33], v[222:225], v[246:249], v[18:33]
	v_pk_add_f32 v[174:175], v[174:175], v[174:175] op_sel_hi:[0,1]
	v_mov_b32_e32 v201, v175
	s_waitcnt lgkmcnt(4)
	v_mfma_f32_32x32x16_bf16 v[2:17], v[238:241], v[246:249], v[2:17]
	s_waitcnt lgkmcnt(2)
	v_mfma_f32_32x32x16_bf16 v[18:33], v[162:165], v[250:253], v[18:33]
	v_add_f32_e64 v162, v190, v200
	v_add_f32_e64 v163, v191, v201
	v_pk_add_f32 v[162:163], v[162:163], v[162:163] op_sel_hi:[0,1]
	v_mov_b32_e32 v203, v163
	v_pk_add_f32 v[162:163], v[198:199], v[202:203]
	s_nop 0
	v_add_f32_e32 v210, v162, v163
	v_fmac_f32_e32 v210, v218, v172
	s_waitcnt lgkmcnt(0)
	v_mfma_f32_32x32x16_bf16 v[2:17], v[242:245], v[250:253], v[2:17]
	s_cbranch_execz .LBB0_483
